# S5-in and QKV GEMM epilogues: row scales of a tile read from LDS together (as in gate/up)
# speedup vs baseline: 1.0069x; 1.0069x over previous
.LBB0_165:
	s_andn2_b64 vcc, exec, s[22:23]
	s_cbranch_vccnz .LBB0_167
	ds_read_b32 v140, v143
	ds_read_b32 v215, v143 offset:64
	ds_read_b32 v216, v143 offset:128
	ds_read_b32 v217, v143 offset:192
	ds_read_b32 v218, v143 offset:512
	ds_read_b32 v219, v143 offset:576
	ds_read_b32 v220, v143 offset:640
	ds_read_b32 v221, v143 offset:704

.LBB0_169:
	s_andn2_b64 vcc, exec, s[20:21]
	s_cbranch_vccnz .LBB0_171
	v_mov_b32_e32 v114, v215

.LBB0_173:
	s_andn2_b64 vcc, exec, s[20:21]
	s_cbranch_vccnz .LBB0_175
	v_mov_b32_e32 v98, v216

.LBB0_177:
	s_andn2_b64 vcc, exec, s[20:21]
	s_cbranch_vccnz .LBB0_179
	v_mov_b32_e32 v82, v217

.LBB0_181:
	s_andn2_b64 vcc, exec, s[20:21]
	s_cbranch_vccnz .LBB0_183
	v_mov_b32_e32 v66, v218

.LBB0_185:
	s_andn2_b64 vcc, exec, s[20:21]
	s_cbranch_vccnz .LBB0_187
	v_mov_b32_e32 v50, v219

.LBB0_189:
	s_andn2_b64 vcc, exec, s[20:21]
	s_cbranch_vccnz .LBB0_191
	v_mov_b32_e32 v34, v220

.LBB0_193:
	s_andn2_b64 vcc, exec, s[8:9]
	s_cbranch_vccnz .LBB0_154
	v_mov_b32_e32 v18, v221
	s_branch .LBB0_154

.LBB0_537:
	s_andn2_b64 vcc, exec, s[24:25]
	s_cbranch_vccnz .LBB0_539
	ds_read_b32 v140, v144
	ds_read_b32 v215, v144 offset:64
	ds_read_b32 v216, v144 offset:128
	ds_read_b32 v217, v144 offset:192
	ds_read_b32 v218, v144 offset:512
	ds_read_b32 v219, v144 offset:576
	ds_read_b32 v220, v144 offset:640
	ds_read_b32 v221, v144 offset:704

.LBB0_541:
	s_andn2_b64 vcc, exec, s[22:23]
	s_cbranch_vccnz .LBB0_543
	v_mov_b32_e32 v114, v215

.LBB0_545:
	s_andn2_b64 vcc, exec, s[22:23]
	s_cbranch_vccnz .LBB0_547
	v_mov_b32_e32 v98, v216

.LBB0_549:
	s_andn2_b64 vcc, exec, s[22:23]
	s_cbranch_vccnz .LBB0_551
	v_mov_b32_e32 v82, v217

.LBB0_553:
	s_andn2_b64 vcc, exec, s[22:23]
	s_cbranch_vccnz .LBB0_555
	v_mov_b32_e32 v66, v218

.LBB0_557:
	s_andn2_b64 vcc, exec, s[22:23]
	s_cbranch_vccnz .LBB0_559
	v_mov_b32_e32 v50, v219

.LBB0_561:
	s_andn2_b64 vcc, exec, s[22:23]
	s_cbranch_vccnz .LBB0_563
	v_mov_b32_e32 v34, v220
